# cmb phase: two items per trip, 14 loads issued a full trip ahead (latency of ~2 us per item was exposed with one-item lookahead)
# baseline (speedup 1.0000x reference)
; DI void phase_cmb(const Params& P) {
;     ...
;     for (int idx = blockIdx.x * NTHR + tid; idx < HT * 96; idx += gridDim.x * NTHR) {
;         const int row = idx / 96, c8 = idx % 96; const int head = c8 >> 3;
;         float l0 = pbl[((size_t)0 * HT + row) * 12 + head], l1 = pbl[((size_t)1 * HT + row) * 12 + head], l2 = pbl[((size_t)2 * HT + row) * 12 + head];
;         float mx = fmaxf(l0, fmaxf(l1, l2));
;         float w0 = __expf(l0 - mx), w1 = __expf(l1 - mx), w2 = __expf(l2 - mx);
;         const float inv = 1.f / (w0 + w1 + w2); w0 *= inv; w1 *= inv; w2 *= inv;
;         u32x4 a = *(const u32x4*)(pbo + ((size_t)0 * HT + row) * 768 + c8 * 8);
;         u32x4 b = *(const u32x4*)(pbo + ((size_t)1 * HT + row) * 768 + c8 * 8);
;         u32x4 c = *(const u32x4*)(pbo + ((size_t)2 * HT + row) * 768 + c8 * 8);
;         u32x4 z = *(const u32x4*)(Ph + (size_t)row * PO + OFF_Z + 768 + c8 * 8);
.LBB0_322:
	s_or_b64 exec, exec, s[0:1]
	v_readlane_b32 s0, v237, 12
	v_readlane_b32 s2, v237, 14
	v_readlane_b32 s3, v237, 15
	v_readlane_b32 s4, v237, 16
	v_readlane_b32 s5, v237, 17
	v_readlane_b32 s6, v237, 18
	v_readlane_b32 s7, v237, 19
	v_readlane_b32 s1, v237, 13
	s_mov_b64 s[8:9], s[60:61]
	s_mov_b64 s[2:3], s[24:25]
	s_mov_b64 s[4:5], s[38:39]
	s_mov_b64 s[6:7], s[98:99]
	s_mov_b64 s[10:11], s[28:29]
	s_waitcnt lgkmcnt(0)
	s_barrier
	v_mov_b32_e32 v2, v174
	v_readlane_b32 s0, v237, 20
	s_nop 1
	v_add_u32_e32 v0, s0, v2
	v_cmp_gt_i32_e32 vcc, s40, v0
	s_and_saveexec_b64 s[0:1], vcc
	s_cbranch_execz .LBB0_325
	s_add_u32 s4, s8, 0xcf40000
	s_addc_u32 s5, s9, 0
	s_add_u32 s6, s8, 0x8500000
	s_addc_u32 s7, s9, 0
	s_add_u32 s8, s8, 0xcd00000
	v_readlane_b32 s2, v236, 17
	s_addc_u32 s9, s9, 0
	s_mov_b64 s[10:11], 0
	v_lshl_add_u32 v2, v2, 3, s2
	s_lshl_b32 s2, s16, 3
	s_mov_b32 s3, 0x2aaaaaab
	v_mul_hi_i32 v37, v0, s3
	v_lshrrev_b32_e32 v38, 31, v37
	v_ashrrev_i32_e32 v37, 4, v37
	v_add_u32_e32 v37, v37, v38
	s_movk_i32 s3, 0xffa0
	v_mad_u64_u32 v[38:39], vcc, v37, s3, v[0:1]
	v_ashrrev_i32_e32 v38, 3, v38
	v_ashrrev_i32_e32 v39, 31, v38
	v_mad_i64_i32 v[40:41], vcc, v37, 48, s[8:9]
	v_lshl_add_u64 v[38:39], v[38:39], 2, v[40:41]
	s_mov_b32 s3, 0xc0000
	v_add_co_u32_e32 v40, vcc, s3, v38
	global_load_dword v48, v[38:39], off
	s_nop 0
	v_addc_co_u32_e32 v41, vcc, 0, v39, vcc
	global_load_dword v49, v[40:41], off
	v_add_co_u32_e32 v38, vcc, s40, v38
	s_nop 1
	v_addc_co_u32_e32 v39, vcc, 0, v39, vcc
	global_load_dword v50, v[38:39], off
	v_mov_b64_e32 v[42:43], s[4:5]
	v_mad_i64_i32 v[42:43], vcc, v37, s52, v[42:43]
	s_movk_i32 s3, 0xfd00
	v_mad_u64_u32 v[44:45], vcc, v37, s3, v[2:3]
	v_mov_b64_e32 v[46:47], s[6:7]
	v_ashrrev_i32_e32 v45, 31, v44
	v_mad_i64_i32 v[46:47], vcc, v37, s42, v[46:47]
	v_lshlrev_b64 v[44:45], 1, v[44:45]
	v_lshl_add_u64 v[46:47], v[46:47], 0, v[44:45]
	global_load_dwordx4 v[52:55], v[46:47], off
	s_mov_b32 s3, 0x1800000
	v_add_co_u32_e32 v40, vcc, s3, v46
	s_nop 1
	v_addc_co_u32_e32 v41, vcc, 0, v47, vcc
	global_load_dwordx4 v[56:59], v[40:41], off
	s_mov_b32 s3, 0x3000000
	v_add_co_u32_e32 v40, vcc, s3, v46
	s_nop 1
	v_addc_co_u32_e32 v41, vcc, 0, v47, vcc
	global_load_dwordx4 v[60:63], v[40:41], off
	v_lshl_add_u64 v[68:69], v[42:43], 0, v[44:45]
	s_movk_i32 s3, 0x2000
	v_add_co_u32_e32 v40, vcc, s3, v68
	s_nop 1
	v_addc_co_u32_e32 v41, vcc, 0, v69, vcc
	global_load_dwordx4 v[64:67], v[40:41], off offset:3328
	v_add_u32_e32 v34, s16, v0
	v_mov_b32_e32 v35, 0
	v_add_u32_e32 v114, s2, v2
	s_mov_b32 s3, 0x2aaaaaab
	v_mul_hi_i32 v37, v34, s3
	v_lshrrev_b32_e32 v38, 31, v37
	v_ashrrev_i32_e32 v37, 4, v37
	v_add_u32_e32 v37, v37, v38
	s_movk_i32 s3, 0xffa0
	v_mad_u64_u32 v[38:39], vcc, v37, s3, v[34:35]
	v_ashrrev_i32_e32 v38, 3, v38
	v_ashrrev_i32_e32 v39, 31, v38
	v_mad_i64_i32 v[40:41], vcc, v37, 48, s[8:9]
	v_lshl_add_u64 v[38:39], v[38:39], 2, v[40:41]
	s_mov_b32 s3, 0xc0000
	v_add_co_u32_e32 v40, vcc, s3, v38
	global_load_dword v70, v[38:39], off
	s_nop 0
	v_addc_co_u32_e32 v41, vcc, 0, v39, vcc
	global_load_dword v71, v[40:41], off
	v_add_co_u32_e32 v38, vcc, s40, v38
	s_nop 1
	v_addc_co_u32_e32 v39, vcc, 0, v39, vcc
	global_load_dword v72, v[38:39], off
	v_mov_b64_e32 v[42:43], s[4:5]
	v_mad_i64_i32 v[42:43], vcc, v37, s52, v[42:43]
	s_movk_i32 s3, 0xfd00
	v_mad_u64_u32 v[44:45], vcc, v37, s3, v[114:115]
	v_mov_b64_e32 v[46:47], s[6:7]
	v_ashrrev_i32_e32 v45, 31, v44
	v_mad_i64_i32 v[46:47], vcc, v37, s42, v[46:47]
	v_lshlrev_b64 v[44:45], 1, v[44:45]
	v_lshl_add_u64 v[46:47], v[46:47], 0, v[44:45]
	global_load_dwordx4 v[74:77], v[46:47], off
	s_mov_b32 s3, 0x1800000
	v_add_co_u32_e32 v40, vcc, s3, v46
	s_nop 1
	v_addc_co_u32_e32 v41, vcc, 0, v47, vcc
	global_load_dwordx4 v[78:81], v[40:41], off
	s_mov_b32 s3, 0x3000000
	v_add_co_u32_e32 v40, vcc, s3, v46
	s_nop 1
	v_addc_co_u32_e32 v41, vcc, 0, v47, vcc
	global_load_dwordx4 v[82:85], v[40:41], off
	v_lshl_add_u64 v[90:91], v[42:43], 0, v[44:45]
	s_movk_i32 s3, 0x2000
	v_add_co_u32_e32 v40, vcc, s3, v90
	s_nop 1
	v_addc_co_u32_e32 v41, vcc, 0, v91, vcc
	global_load_dwordx4 v[86:89], v[40:41], off offset:3328
.LBB0_324:
	s_waitcnt vmcnt(0)
	v_mov_b32_e32 v8, v48
	v_mov_b32_e32 v6, v49
	v_mov_b32_e32 v4, v50
	v_mov_b64_e32 v[10:11], v[52:53]
	v_mov_b64_e32 v[12:13], v[54:55]
	v_mov_b64_e32 v[14:15], v[56:57]
	v_mov_b64_e32 v[16:17], v[58:59]
	v_mov_b64_e32 v[18:19], v[60:61]
	v_mov_b64_e32 v[20:21], v[62:63]
	v_mov_b64_e32 v[22:23], v[64:65]
	v_mov_b64_e32 v[24:25], v[66:67]
	v_mov_b64_e32 v[26:27], v[68:69]
	v_mov_b64_e32 v[92:93], v[70:71]
	v_mov_b64_e32 v[94:95], v[72:73]
	v_mov_b64_e32 v[96:97], v[74:75]
	v_mov_b64_e32 v[98:99], v[76:77]
	v_mov_b64_e32 v[100:101], v[78:79]
	v_mov_b64_e32 v[102:103], v[80:81]
	v_mov_b64_e32 v[104:105], v[82:83]
	v_mov_b64_e32 v[106:107], v[84:85]
	v_mov_b64_e32 v[108:109], v[86:87]
	v_mov_b64_e32 v[110:111], v[88:89]
	v_mov_b64_e32 v[112:113], v[90:91]
	v_add_u32_e32 v0, s16, v0
	v_add_u32_e32 v0, s16, v0
	v_add_u32_e32 v2, s2, v2
	v_add_u32_e32 v2, s2, v2
	s_mov_b32 s3, 0x17ffff
	v_cmp_ge_i32_e32 vcc, s3, v0
	s_and_saveexec_b64 s[12:13], vcc
	s_cbranch_execz .Lcmb_nopf
; DI float bflo(unsigned u) { return __uint_as_float(u << 16); }
; DI float silu_f(float z) { return z / (1.f + __expf(-z)); }
; DI void phase_cmb(const Params& P) {
;     ...
;         const int row = idx / 96, c8 = idx % 96; const int head = c8 >> 3;
;         float l0 = pbl[((size_t)0 * HT + row) * 12 + head], l1 = pbl[((size_t)1 * HT + row) * 12 + head], l2 = pbl[((size_t)2 * HT + row) * 12 + head];
;         float mx = fmaxf(l0, fmaxf(l1, l2));
;         float w0 = __expf(l0 - mx), w1 = __expf(l1 - mx), w2 = __expf(l2 - mx);
;         const float inv = 1.f / (w0 + w1 + w2); w0 *= inv; w1 *= inv; w2 *= inv;
;         u32x4 a = *(const u32x4*)(pbo + ((size_t)0 * HT + row) * 768 + c8 * 8);
;         u32x4 b = *(const u32x4*)(pbo + ((size_t)1 * HT + row) * 768 + c8 * 8);
;         u32x4 c = *(const u32x4*)(pbo + ((size_t)2 * HT + row) * 768 + c8 * 8);
;         u32x4 z = *(const u32x4*)(Ph + (size_t)row * PO + OFF_Z + 768 + c8 * 8);
;         u32x4 o;
; #pragma unroll
;         for (int j = 0; j < 4; ++j) {
;             float lo = (w0 * bflo(a[j]) + w1 * bflo(b[j]) + w2 * bflo(c[j])) * silu_f(bflo(z[j]));
	s_mov_b32 s3, 0x2aaaaaab
	v_mul_hi_i32 v37, v0, s3
	v_lshrrev_b32_e32 v38, 31, v37
	v_ashrrev_i32_e32 v37, 4, v37
	v_add_u32_e32 v37, v37, v38
	s_movk_i32 s3, 0xffa0
	v_mad_u64_u32 v[38:39], vcc, v37, s3, v[0:1]
	v_ashrrev_i32_e32 v38, 3, v38
	v_ashrrev_i32_e32 v39, 31, v38
	v_mad_i64_i32 v[40:41], vcc, v37, 48, s[8:9]
	v_lshl_add_u64 v[38:39], v[38:39], 2, v[40:41]
	s_mov_b32 s3, 0xc0000
	v_add_co_u32_e32 v40, vcc, s3, v38
	global_load_dword v48, v[38:39], off
	s_nop 0
	v_addc_co_u32_e32 v41, vcc, 0, v39, vcc
	global_load_dword v49, v[40:41], off
	v_add_co_u32_e32 v38, vcc, s40, v38
	s_nop 1
	v_addc_co_u32_e32 v39, vcc, 0, v39, vcc
	global_load_dword v50, v[38:39], off
	v_mov_b64_e32 v[42:43], s[4:5]
	v_mad_i64_i32 v[42:43], vcc, v37, s52, v[42:43]
	s_movk_i32 s3, 0xfd00
	v_mad_u64_u32 v[44:45], vcc, v37, s3, v[2:3]
	v_mov_b64_e32 v[46:47], s[6:7]
	v_ashrrev_i32_e32 v45, 31, v44
	v_mad_i64_i32 v[46:47], vcc, v37, s42, v[46:47]
	v_lshlrev_b64 v[44:45], 1, v[44:45]
	v_lshl_add_u64 v[46:47], v[46:47], 0, v[44:45]
	global_load_dwordx4 v[52:55], v[46:47], off
	s_mov_b32 s3, 0x1800000
	v_add_co_u32_e32 v40, vcc, s3, v46
	s_nop 1
	v_addc_co_u32_e32 v41, vcc, 0, v47, vcc
	global_load_dwordx4 v[56:59], v[40:41], off
	s_mov_b32 s3, 0x3000000
	v_add_co_u32_e32 v40, vcc, s3, v46
	s_nop 1
	v_addc_co_u32_e32 v41, vcc, 0, v47, vcc
	global_load_dwordx4 v[60:63], v[40:41], off
	v_lshl_add_u64 v[68:69], v[42:43], 0, v[44:45]
	s_movk_i32 s3, 0x2000
	v_add_co_u32_e32 v40, vcc, s3, v68
	s_nop 1
	v_addc_co_u32_e32 v41, vcc, 0, v69, vcc
	global_load_dwordx4 v[64:67], v[40:41], off offset:3328
	v_add_u32_e32 v34, s16, v0
	v_mov_b32_e32 v35, 0
	v_add_u32_e32 v114, s2, v2
	s_mov_b32 s3, 0x2aaaaaab
	v_mul_hi_i32 v37, v34, s3
	v_lshrrev_b32_e32 v38, 31, v37
	v_ashrrev_i32_e32 v37, 4, v37
	v_add_u32_e32 v37, v37, v38
	s_movk_i32 s3, 0xffa0
	v_mad_u64_u32 v[38:39], vcc, v37, s3, v[34:35]
	v_ashrrev_i32_e32 v38, 3, v38
	v_ashrrev_i32_e32 v39, 31, v38
	v_mad_i64_i32 v[40:41], vcc, v37, 48, s[8:9]
	v_lshl_add_u64 v[38:39], v[38:39], 2, v[40:41]
	s_mov_b32 s3, 0xc0000
	v_add_co_u32_e32 v40, vcc, s3, v38
	global_load_dword v70, v[38:39], off
	s_nop 0
	v_addc_co_u32_e32 v41, vcc, 0, v39, vcc
	global_load_dword v71, v[40:41], off
	v_add_co_u32_e32 v38, vcc, s40, v38
	s_nop 1
	v_addc_co_u32_e32 v39, vcc, 0, v39, vcc
	global_load_dword v72, v[38:39], off
	v_mov_b64_e32 v[42:43], s[4:5]
	v_mad_i64_i32 v[42:43], vcc, v37, s52, v[42:43]
	s_movk_i32 s3, 0xfd00
	v_mad_u64_u32 v[44:45], vcc, v37, s3, v[114:115]
	v_mov_b64_e32 v[46:47], s[6:7]
	v_ashrrev_i32_e32 v45, 31, v44
	v_mad_i64_i32 v[46:47], vcc, v37, s42, v[46:47]
	v_lshlrev_b64 v[44:45], 1, v[44:45]
	v_lshl_add_u64 v[46:47], v[46:47], 0, v[44:45]
	global_load_dwordx4 v[74:77], v[46:47], off
	s_mov_b32 s3, 0x1800000
	v_add_co_u32_e32 v40, vcc, s3, v46
	s_nop 1
	v_addc_co_u32_e32 v41, vcc, 0, v47, vcc
	global_load_dwordx4 v[78:81], v[40:41], off
	s_mov_b32 s3, 0x3000000
	v_add_co_u32_e32 v40, vcc, s3, v46
	s_nop 1
	v_addc_co_u32_e32 v41, vcc, 0, v47, vcc
	global_load_dwordx4 v[82:85], v[40:41], off
	v_lshl_add_u64 v[90:91], v[42:43], 0, v[44:45]
	s_movk_i32 s3, 0x2000
	v_add_co_u32_e32 v40, vcc, s3, v90
	s_nop 1
	v_addc_co_u32_e32 v41, vcc, 0, v91, vcc
	global_load_dwordx4 v[86:89], v[40:41], off offset:3328
.Lcmb_nopf:
	s_or_b64 exec, exec, s[12:13]
	v_max3_f32 v5, v8, v6, v4
	v_sub_f32_e32 v7, v8, v5
	v_sub_f32_e32 v6, v6, v5
	v_mul_f32_e32 v7, 0x3fb8aa3b, v7
	v_mul_f32_e32 v6, 0x3fb8aa3b, v6
	v_sub_f32_e32 v4, v4, v5
	v_exp_f32_e32 v7, v7
	v_exp_f32_e32 v6, v6
	v_mul_f32_e32 v4, 0x3fb8aa3b, v4
	v_exp_f32_e32 v4, v4
	v_add_f32_e32 v5, v7, v6
	v_add_f32_e32 v5, v4, v5
	v_div_scale_f32 v8, s[12:13], v5, v5, 1.0
	v_rcp_f32_e32 v9, v8
	s_nop 0
	v_fma_f32 v30, -v8, v9, 1.0
	v_fmac_f32_e32 v9, v30, v9
	v_div_scale_f32 v30, vcc, 1.0, v5, 1.0
	v_mul_f32_e32 v31, v30, v9
	v_fma_f32 v32, -v8, v31, v30
	v_fmac_f32_e32 v31, v32, v9
	v_fma_f32 v8, -v8, v31, v30
	v_div_fmas_f32 v8, v8, v9, v31
	v_div_fixup_f32 v8, v8, v5, 1.0
	v_pk_mul_f32 v[28:29], v[6:7], v[8:9] op_sel_hi:[1,0]
	v_mul_f32_e32 v4, v4, v8
	v_and_b32_e32 v9, 0xffff0000, v10
	v_lshlrev_b32_e32 v30, 16, v10
	v_lshlrev_b32_e32 v8, 16, v14
	v_and_b32_e32 v31, 0xffff0000, v14
	v_pk_mul_f32 v[30:31], v[28:29], v[30:31] op_sel:[1,0] op_sel_hi:[0,1]
	v_pk_fma_f32 v[8:9], v[28:29], v[8:9], v[30:31]
	v_lshlrev_b32_e32 v32, 16, v18
	v_and_b32_e32 v33, 0xffff0000, v18
	v_lshlrev_b32_e32 v3, 16, v22
	v_and_b32_e32 v5, 0xffff0000, v22
	v_mul_f32_e32 v6, 0xbfb8aa3b, v3
	v_mul_f32_e32 v7, 0xbfb8aa3b, v5
	v_exp_f32_e32 v6, v6
	v_exp_f32_e32 v7, v7
	s_nop 0
	v_pk_add_f32 v[6:7], v[6:7], 1.0 op_sel_hi:[1,0]
	s_nop 0
	v_div_scale_f32 v10, s[12:13], v7, v7, v5
	v_rcp_f32_e32 v14, v10
	s_nop 0
	v_fma_f32 v18, -v10, v14, 1.0
	v_fmac_f32_e32 v14, v18, v14
	v_div_scale_f32 v18, vcc, v5, v7, v5
	v_mul_f32_e32 v22, v18, v14
	v_fma_f32 v34, -v10, v22, v18
	v_fmac_f32_e32 v22, v34, v14
	v_fma_f32 v10, -v10, v22, v18
	v_div_fmas_f32 v10, v10, v14, v22
	v_div_fixup_f32 v7, v10, v7, v5
	v_div_scale_f32 v5, s[12:13], v6, v6, v3
	v_rcp_f32_e32 v10, v5
	s_nop 0
	v_fma_f32 v14, -v5, v10, 1.0
	v_fmac_f32_e32 v10, v14, v10
	v_div_scale_f32 v14, vcc, v3, v6, v3
	v_mul_f32_e32 v18, v14, v10
	v_fma_f32 v22, -v5, v18, v14
	v_fmac_f32_e32 v18, v22, v10
	v_fma_f32 v5, -v5, v18, v14
	v_div_fmas_f32 v5, v5, v10, v18
	v_div_fixup_f32 v6, v5, v6, v3
	v_pk_fma_f32 v[8:9], v[4:5], v[32:33], v[8:9] op_sel_hi:[0,1,1]
	v_pk_mul_f32 v[6:7], v[6:7], v[8:9]
	v_lshlrev_b32_e32 v3, 16, v23
	v_cvt_pk_bf16_f32 v6, v6, v7
	v_and_b32_e32 v5, 0xffff0000, v23
	v_mul_f32_e32 v7, 0xbfb8aa3b, v3
	v_exp_f32_e32 v8, v7
; DI unsigned pk2(float lo, float hi) { fl2_t f = {lo, hi}; bf2_t b = __builtin_convertvector(f, bf2_t); return __builtin_bit_cast(unsigned, b); }
; DI float bflo(unsigned u) { return __uint_as_float(u << 16); }
; DI float bfhi(unsigned u) { return __uint_as_float(u & 0xffff0000u); }
; DI float silu_f(float z) { return z / (1.f + __expf(-z)); }
; DI void phase_cmb(const Params& P) {
;     ...
;         float mx = fmaxf(l0, fmaxf(l1, l2));
;         float w0 = __expf(l0 - mx), w1 = __expf(l1 - mx), w2 = __expf(l2 - mx);
;         const float inv = 1.f / (w0 + w1 + w2); w0 *= inv; w1 *= inv; w2 *= inv;
;         u32x4 a = *(const u32x4*)(pbo + ((size_t)0 * HT + row) * 768 + c8 * 8);
;         u32x4 b = *(const u32x4*)(pbo + ((size_t)1 * HT + row) * 768 + c8 * 8);
;         u32x4 c = *(const u32x4*)(pbo + ((size_t)2 * HT + row) * 768 + c8 * 8);
;         u32x4 z = *(const u32x4*)(Ph + (size_t)row * PO + OFF_Z + 768 + c8 * 8);
;         u32x4 o;
; #pragma unroll
;         for (int j = 0; j < 4; ++j) {
;             float lo = (w0 * bflo(a[j]) + w1 * bflo(b[j]) + w2 * bflo(c[j])) * silu_f(bflo(z[j]));
;             float hi = (w0 * bfhi(a[j]) + w1 * bfhi(b[j]) + w2 * bfhi(c[j])) * silu_f(bfhi(z[j]));
;             o[j] = pk2(lo, hi);
;         }
;         *(u32x4*)(Ph + (size_t)row * PO + OFF_BQ + c8 * 8) = o;
	v_mul_f32_e32 v7, 0xbfb8aa3b, v5
	v_exp_f32_e32 v9, v7
	v_lshlrev_b32_e32 v22, 16, v15
	v_and_b32_e32 v23, 0xffff0000, v11
	v_lshlrev_b32_e32 v10, 16, v11
	v_pk_add_f32 v[8:9], v[8:9], 1.0 op_sel_hi:[1,0]
	v_and_b32_e32 v11, 0xffff0000, v15
	v_div_scale_f32 v7, s[12:13], v9, v9, v5
	v_rcp_f32_e32 v18, v7
	v_lshlrev_b32_e32 v14, 16, v19
	v_and_b32_e32 v15, 0xffff0000, v19
	v_pk_mul_f32 v[10:11], v[28:29], v[10:11] op_sel:[1,0] op_sel_hi:[0,1]
	v_fma_f32 v19, -v7, v18, 1.0
	v_fmac_f32_e32 v18, v19, v18
	v_div_scale_f32 v19, vcc, v5, v9, v5
	v_mul_f32_e32 v30, v19, v18
	v_fma_f32 v31, -v7, v30, v19
	v_fmac_f32_e32 v30, v31, v18
	v_fma_f32 v7, -v7, v30, v19
	v_div_fmas_f32 v7, v7, v18, v30
	v_div_fixup_f32 v9, v7, v9, v5
	v_div_scale_f32 v5, s[12:13], v8, v8, v3
	v_rcp_f32_e32 v7, v5
	v_pk_fma_f32 v[10:11], v[28:29], v[22:23], v[10:11]
	v_fma_f32 v18, -v5, v7, 1.0
	v_fmac_f32_e32 v7, v18, v7
	v_div_scale_f32 v18, vcc, v3, v8, v3
	v_mul_f32_e32 v19, v18, v7
	v_fma_f32 v30, -v5, v19, v18
	v_fmac_f32_e32 v19, v30, v7
	v_fma_f32 v5, -v5, v19, v18
	v_div_fmas_f32 v5, v5, v7, v19
	v_div_fixup_f32 v8, v5, v8, v3
	v_pk_fma_f32 v[10:11], v[4:5], v[14:15], v[10:11] op_sel_hi:[0,1,1]
	v_pk_mul_f32 v[8:9], v[8:9], v[10:11]
	v_lshlrev_b32_e32 v3, 16, v24
	v_and_b32_e32 v5, 0xffff0000, v24
	v_cvt_pk_bf16_f32 v7, v8, v9
	v_mul_f32_e32 v8, 0xbfb8aa3b, v3
	v_mul_f32_e32 v9, 0xbfb8aa3b, v5
	v_exp_f32_e32 v8, v8
	v_exp_f32_e32 v9, v9
	v_and_b32_e32 v11, 0xffff0000, v12
	v_lshlrev_b32_e32 v14, 16, v12
	v_lshlrev_b32_e32 v10, 16, v16
	v_pk_add_f32 v[8:9], v[8:9], 1.0 op_sel_hi:[1,0]
	v_and_b32_e32 v15, 0xffff0000, v16
	v_div_scale_f32 v12, s[12:13], v9, v9, v5
	v_rcp_f32_e32 v16, v12
	v_lshlrev_b32_e32 v18, 16, v20
	v_and_b32_e32 v19, 0xffff0000, v20
	v_pk_mul_f32 v[14:15], v[28:29], v[14:15] op_sel:[1,0] op_sel_hi:[0,1]
	v_fma_f32 v20, -v12, v16, 1.0
	v_fmac_f32_e32 v16, v20, v16
	v_div_scale_f32 v20, vcc, v5, v9, v5
	v_mul_f32_e32 v22, v20, v16
	v_fma_f32 v23, -v12, v22, v20
	v_fmac_f32_e32 v22, v23, v16
	v_fma_f32 v12, -v12, v22, v20
	v_div_fmas_f32 v12, v12, v16, v22
	v_div_fixup_f32 v9, v12, v9, v5
	v_div_scale_f32 v5, s[12:13], v8, v8, v3
	v_rcp_f32_e32 v12, v5
	v_pk_fma_f32 v[10:11], v[28:29], v[10:11], v[14:15]
	v_and_b32_e32 v15, 0xffff0000, v13
	v_lshlrev_b32_e32 v14, 16, v17
	v_fma_f32 v16, -v5, v12, 1.0
	v_fmac_f32_e32 v12, v16, v12
	v_div_scale_f32 v16, vcc, v3, v8, v3
	v_mul_f32_e32 v20, v16, v12
	v_fma_f32 v22, -v5, v20, v16
	v_fmac_f32_e32 v20, v22, v12
	v_fma_f32 v5, -v5, v20, v16
	v_div_fmas_f32 v5, v5, v12, v20
	v_div_fixup_f32 v8, v5, v8, v3
	v_pk_fma_f32 v[10:11], v[4:5], v[18:19], v[10:11] op_sel_hi:[0,1,1]
	v_pk_mul_f32 v[8:9], v[8:9], v[10:11]
	v_lshlrev_b32_e32 v3, 16, v25
	v_cvt_pk_bf16_f32 v8, v8, v9
	v_and_b32_e32 v9, 0xffff0000, v25
	v_mul_f32_e32 v5, 0xbfb8aa3b, v3
	v_mul_f32_e32 v11, 0xbfb8aa3b, v9
	v_exp_f32_e32 v10, v5
	v_exp_f32_e32 v11, v11
	v_lshlrev_b32_e32 v12, 16, v13
	v_and_b32_e32 v13, 0xffff0000, v17
	v_pk_mul_f32 v[12:13], v[28:29], v[12:13] op_sel:[1,0] op_sel_hi:[0,1]
	v_pk_fma_f32 v[12:13], v[28:29], v[14:15], v[12:13]
	v_lshlrev_b32_e32 v14, 16, v21
	v_and_b32_e32 v15, 0xffff0000, v21
	v_pk_add_f32 v[10:11], v[10:11], 1.0 op_sel_hi:[1,0]
	v_pk_fma_f32 v[4:5], v[4:5], v[14:15], v[12:13] op_sel_hi:[0,1,1]
	v_div_scale_f32 v12, s[12:13], v11, v11, v9
	v_rcp_f32_e32 v13, v12
	s_nop 0
	v_fma_f32 v14, -v12, v13, 1.0
	v_fmac_f32_e32 v13, v14, v13
	v_div_scale_f32 v14, vcc, v9, v11, v9
	v_mul_f32_e32 v15, v14, v13
	v_fma_f32 v16, -v12, v15, v14
	v_fmac_f32_e32 v15, v16, v13
	v_fma_f32 v12, -v12, v15, v14
	v_div_fmas_f32 v12, v12, v13, v15
	v_div_fixup_f32 v11, v12, v11, v9
	v_div_scale_f32 v9, s[12:13], v10, v10, v3
	v_rcp_f32_e32 v12, v9
	s_nop 0
	v_fma_f32 v13, -v9, v12, 1.0
	v_fmac_f32_e32 v12, v13, v12
	v_div_scale_f32 v13, vcc, v3, v10, v3
	v_mul_f32_e32 v14, v13, v12
	v_fma_f32 v15, -v9, v14, v13
	v_fmac_f32_e32 v14, v15, v12
	v_fma_f32 v9, -v9, v14, v13
	v_div_fmas_f32 v9, v9, v12, v14
	v_div_fixup_f32 v10, v9, v10, v3
	v_pk_mul_f32 v[4:5], v[10:11], v[4:5]
	v_cvt_pk_bf16_f32 v9, v4, v5
	global_store_dwordx4 v[26:27], v[6:9], off offset:2304
	s_nop 2
	v_mov_b32_e32 v8, v92
	v_mov_b32_e32 v6, v93
	v_mov_b32_e32 v4, v94
	v_mov_b64_e32 v[10:11], v[96:97]
	v_mov_b64_e32 v[12:13], v[98:99]
	v_mov_b64_e32 v[14:15], v[100:101]
	v_mov_b64_e32 v[16:17], v[102:103]
	v_mov_b64_e32 v[18:19], v[104:105]
	v_mov_b64_e32 v[20:21], v[106:107]
	v_mov_b64_e32 v[22:23], v[108:109]
	v_mov_b64_e32 v[24:25], v[110:111]
	v_mov_b64_e32 v[26:27], v[112:113]
	v_max3_f32 v5, v8, v6, v4
	v_sub_f32_e32 v7, v8, v5
	v_sub_f32_e32 v6, v6, v5
	v_mul_f32_e32 v7, 0x3fb8aa3b, v7
	v_mul_f32_e32 v6, 0x3fb8aa3b, v6
	v_sub_f32_e32 v4, v4, v5
	v_exp_f32_e32 v7, v7
	v_exp_f32_e32 v6, v6
	v_mul_f32_e32 v4, 0x3fb8aa3b, v4
	v_exp_f32_e32 v4, v4
	v_add_f32_e32 v5, v7, v6
	v_add_f32_e32 v5, v4, v5
	v_div_scale_f32 v8, s[12:13], v5, v5, 1.0
	v_rcp_f32_e32 v9, v8
	s_nop 0
	v_fma_f32 v30, -v8, v9, 1.0
	v_fmac_f32_e32 v9, v30, v9
	v_div_scale_f32 v30, vcc, 1.0, v5, 1.0
	v_mul_f32_e32 v31, v30, v9
	v_fma_f32 v32, -v8, v31, v30
	v_fmac_f32_e32 v31, v32, v9
	v_fma_f32 v8, -v8, v31, v30
	v_div_fmas_f32 v8, v8, v9, v31
	v_div_fixup_f32 v8, v8, v5, 1.0
	v_pk_mul_f32 v[28:29], v[6:7], v[8:9] op_sel_hi:[1,0]
	v_mul_f32_e32 v4, v4, v8
	v_and_b32_e32 v9, 0xffff0000, v10
	v_lshlrev_b32_e32 v30, 16, v10
	v_lshlrev_b32_e32 v8, 16, v14
	v_and_b32_e32 v31, 0xffff0000, v14
	v_pk_mul_f32 v[30:31], v[28:29], v[30:31] op_sel:[1,0] op_sel_hi:[0,1]
	v_pk_fma_f32 v[8:9], v[28:29], v[8:9], v[30:31]
; DI unsigned pk2(float lo, float hi) { fl2_t f = {lo, hi}; bf2_t b = __builtin_convertvector(f, bf2_t); return __builtin_bit_cast(unsigned, b); }
; DI float bflo(unsigned u) { return __uint_as_float(u << 16); }
; DI float bfhi(unsigned u) { return __uint_as_float(u & 0xffff0000u); }
; DI float silu_f(float z) { return z / (1.f + __expf(-z)); }
; DI void phase_cmb(const Params& P) {
;     ...
; #pragma unroll
;         for (int j = 0; j < 4; ++j) {
;             float lo = (w0 * bflo(a[j]) + w1 * bflo(b[j]) + w2 * bflo(c[j])) * silu_f(bflo(z[j]));
;             float hi = (w0 * bfhi(a[j]) + w1 * bfhi(b[j]) + w2 * bfhi(c[j])) * silu_f(bfhi(z[j]));
;             o[j] = pk2(lo, hi);
;         }
;         *(u32x4*)(Ph + (size_t)row * PO + OFF_BQ + c8 * 8) = o;
;     }
	v_lshlrev_b32_e32 v32, 16, v18
	v_and_b32_e32 v33, 0xffff0000, v18
	v_lshlrev_b32_e32 v3, 16, v22
	v_and_b32_e32 v5, 0xffff0000, v22
	v_mul_f32_e32 v6, 0xbfb8aa3b, v3
	v_mul_f32_e32 v7, 0xbfb8aa3b, v5
	v_exp_f32_e32 v6, v6
	v_exp_f32_e32 v7, v7
	s_nop 0
	v_pk_add_f32 v[6:7], v[6:7], 1.0 op_sel_hi:[1,0]
	s_nop 0
	v_div_scale_f32 v10, s[12:13], v7, v7, v5
	v_rcp_f32_e32 v14, v10
	s_nop 0
	v_fma_f32 v18, -v10, v14, 1.0
	v_fmac_f32_e32 v14, v18, v14
	v_div_scale_f32 v18, vcc, v5, v7, v5
	v_mul_f32_e32 v22, v18, v14
	v_fma_f32 v34, -v10, v22, v18
	v_fmac_f32_e32 v22, v34, v14
	v_fma_f32 v10, -v10, v22, v18
	v_div_fmas_f32 v10, v10, v14, v22
	v_div_fixup_f32 v7, v10, v7, v5
	v_div_scale_f32 v5, s[12:13], v6, v6, v3
	v_rcp_f32_e32 v10, v5
	s_nop 0
	v_fma_f32 v14, -v5, v10, 1.0
	v_fmac_f32_e32 v10, v14, v10
	v_div_scale_f32 v14, vcc, v3, v6, v3
	v_mul_f32_e32 v18, v14, v10
	v_fma_f32 v22, -v5, v18, v14
	v_fmac_f32_e32 v18, v22, v10
	v_fma_f32 v5, -v5, v18, v14
	v_div_fmas_f32 v5, v5, v10, v18
	v_div_fixup_f32 v6, v5, v6, v3
	v_pk_fma_f32 v[8:9], v[4:5], v[32:33], v[8:9] op_sel_hi:[0,1,1]
	v_pk_mul_f32 v[6:7], v[6:7], v[8:9]
	v_lshlrev_b32_e32 v3, 16, v23
	v_cvt_pk_bf16_f32 v6, v6, v7
	v_and_b32_e32 v5, 0xffff0000, v23
	v_mul_f32_e32 v7, 0xbfb8aa3b, v3
	v_exp_f32_e32 v8, v7
	v_mul_f32_e32 v7, 0xbfb8aa3b, v5
	v_exp_f32_e32 v9, v7
	v_lshlrev_b32_e32 v22, 16, v15
	v_and_b32_e32 v23, 0xffff0000, v11
	v_lshlrev_b32_e32 v10, 16, v11
	v_pk_add_f32 v[8:9], v[8:9], 1.0 op_sel_hi:[1,0]
	v_and_b32_e32 v11, 0xffff0000, v15
	v_div_scale_f32 v7, s[12:13], v9, v9, v5
	v_rcp_f32_e32 v18, v7
	v_lshlrev_b32_e32 v14, 16, v19
	v_and_b32_e32 v15, 0xffff0000, v19
	v_pk_mul_f32 v[10:11], v[28:29], v[10:11] op_sel:[1,0] op_sel_hi:[0,1]
	v_fma_f32 v19, -v7, v18, 1.0
	v_fmac_f32_e32 v18, v19, v18
	v_div_scale_f32 v19, vcc, v5, v9, v5
	v_mul_f32_e32 v30, v19, v18
	v_fma_f32 v31, -v7, v30, v19
	v_fmac_f32_e32 v30, v31, v18
	v_fma_f32 v7, -v7, v30, v19
	v_div_fmas_f32 v7, v7, v18, v30
	v_div_fixup_f32 v9, v7, v9, v5
	v_div_scale_f32 v5, s[12:13], v8, v8, v3
	v_rcp_f32_e32 v7, v5
	v_pk_fma_f32 v[10:11], v[28:29], v[22:23], v[10:11]
	v_fma_f32 v18, -v5, v7, 1.0
	v_fmac_f32_e32 v7, v18, v7
	v_div_scale_f32 v18, vcc, v3, v8, v3
	v_mul_f32_e32 v19, v18, v7
	v_fma_f32 v30, -v5, v19, v18
	v_fmac_f32_e32 v19, v30, v7
	v_fma_f32 v5, -v5, v19, v18
	v_div_fmas_f32 v5, v5, v7, v19
	v_div_fixup_f32 v8, v5, v8, v3
	v_pk_fma_f32 v[10:11], v[4:5], v[14:15], v[10:11] op_sel_hi:[0,1,1]
	v_pk_mul_f32 v[8:9], v[8:9], v[10:11]
	v_lshlrev_b32_e32 v3, 16, v24
	v_and_b32_e32 v5, 0xffff0000, v24
	v_cvt_pk_bf16_f32 v7, v8, v9
	v_mul_f32_e32 v8, 0xbfb8aa3b, v3
	v_mul_f32_e32 v9, 0xbfb8aa3b, v5
	v_exp_f32_e32 v8, v8
	v_exp_f32_e32 v9, v9
	v_and_b32_e32 v11, 0xffff0000, v12
	v_lshlrev_b32_e32 v14, 16, v12
	v_lshlrev_b32_e32 v10, 16, v16
	v_pk_add_f32 v[8:9], v[8:9], 1.0 op_sel_hi:[1,0]
	v_and_b32_e32 v15, 0xffff0000, v16
	v_div_scale_f32 v12, s[12:13], v9, v9, v5
	v_rcp_f32_e32 v16, v12
	v_lshlrev_b32_e32 v18, 16, v20
	v_and_b32_e32 v19, 0xffff0000, v20
	v_pk_mul_f32 v[14:15], v[28:29], v[14:15] op_sel:[1,0] op_sel_hi:[0,1]
	v_fma_f32 v20, -v12, v16, 1.0
	v_fmac_f32_e32 v16, v20, v16
	v_div_scale_f32 v20, vcc, v5, v9, v5
	v_mul_f32_e32 v22, v20, v16
	v_fma_f32 v23, -v12, v22, v20
	v_fmac_f32_e32 v22, v23, v16
	v_fma_f32 v12, -v12, v22, v20
	v_div_fmas_f32 v12, v12, v16, v22
	v_div_fixup_f32 v9, v12, v9, v5
	v_div_scale_f32 v5, s[12:13], v8, v8, v3
	v_rcp_f32_e32 v12, v5
	v_pk_fma_f32 v[10:11], v[28:29], v[10:11], v[14:15]
	v_and_b32_e32 v15, 0xffff0000, v13
	v_lshlrev_b32_e32 v14, 16, v17
	v_fma_f32 v16, -v5, v12, 1.0
	v_fmac_f32_e32 v12, v16, v12
	v_div_scale_f32 v16, vcc, v3, v8, v3
	v_mul_f32_e32 v20, v16, v12
	v_fma_f32 v22, -v5, v20, v16
	v_fmac_f32_e32 v20, v22, v12
	v_fma_f32 v5, -v5, v20, v16
	v_div_fmas_f32 v5, v5, v12, v20
	v_div_fixup_f32 v8, v5, v8, v3
	v_pk_fma_f32 v[10:11], v[4:5], v[18:19], v[10:11] op_sel_hi:[0,1,1]
	v_pk_mul_f32 v[8:9], v[8:9], v[10:11]
	v_lshlrev_b32_e32 v3, 16, v25
	v_cvt_pk_bf16_f32 v8, v8, v9
	v_and_b32_e32 v9, 0xffff0000, v25
	v_mul_f32_e32 v5, 0xbfb8aa3b, v3
	v_mul_f32_e32 v11, 0xbfb8aa3b, v9
	v_exp_f32_e32 v10, v5
	v_exp_f32_e32 v11, v11
	v_lshlrev_b32_e32 v12, 16, v13
	v_and_b32_e32 v13, 0xffff0000, v17
	v_pk_mul_f32 v[12:13], v[28:29], v[12:13] op_sel:[1,0] op_sel_hi:[0,1]
	v_pk_fma_f32 v[12:13], v[28:29], v[14:15], v[12:13]
	v_lshlrev_b32_e32 v14, 16, v21
	v_and_b32_e32 v15, 0xffff0000, v21
	v_pk_add_f32 v[10:11], v[10:11], 1.0 op_sel_hi:[1,0]
	v_pk_fma_f32 v[4:5], v[4:5], v[14:15], v[12:13] op_sel_hi:[0,1,1]
	v_div_scale_f32 v12, s[12:13], v11, v11, v9
	v_rcp_f32_e32 v13, v12
	s_nop 0
	v_fma_f32 v14, -v12, v13, 1.0
	v_fmac_f32_e32 v13, v14, v13
	v_div_scale_f32 v14, vcc, v9, v11, v9
	v_mul_f32_e32 v15, v14, v13
	v_fma_f32 v16, -v12, v15, v14
	v_fmac_f32_e32 v15, v16, v13
	v_fma_f32 v12, -v12, v15, v14
	v_div_fmas_f32 v12, v12, v13, v15
	v_div_fixup_f32 v11, v12, v11, v9
	v_div_scale_f32 v9, s[12:13], v10, v10, v3
	v_rcp_f32_e32 v12, v9
	s_nop 0
	v_fma_f32 v13, -v9, v12, 1.0
	v_fmac_f32_e32 v12, v13, v12
	v_div_scale_f32 v13, vcc, v3, v10, v3
	v_mul_f32_e32 v14, v13, v12
	v_fma_f32 v15, -v9, v14, v13
	v_fmac_f32_e32 v14, v15, v12
	v_fma_f32 v9, -v9, v14, v13
	v_div_fmas_f32 v9, v9, v12, v14
	v_div_fixup_f32 v10, v9, v10, v3
	v_pk_mul_f32 v[4:5], v[10:11], v[4:5]
	s_mov_b32 s3, 0x17ffff
	v_cmp_lt_i32_e32 vcc, s3, v0
	v_cvt_pk_bf16_f32 v9, v4, v5
	s_or_b64 s[10:11], vcc, s[10:11]
	global_store_dwordx4 v[26:27], v[6:9], off offset:2304
	s_andn2_b64 exec, exec, s[10:11]
	s_cbranch_execnz .LBB0_324
